# k-loop counter increment and exit compare moved under phase-4 MFMAs; rnn1 clamp fold
# speedup vs baseline: 1.0033x; 1.0019x over previous
; #define PG8_STAGE(bufoff, gbase, voff) do { _Pragma("unroll") for (int _i = 0; _i < 2; ++_i) \
;         __builtin_amdgcn_global_load_lds((const unsigned*)((const char*)(gbase) + (voff)[_i]), (LAS unsigned*)(lds + (bufoff) + ldsw + _i * 8192), 16, 0, 0); } while (0)
; #define PG8_LDA(dst, b, h) do { _Pragma("unroll") for (int m = 0; m < 4; ++m) _Pragma("unroll") for (int k = 0; k < 2; ++k) dst[m][k] = *(const LAS bf16x8*)(lds + PG8_SA(b, h) + aoff + m * 2048 + k * 1024); } while (0)
; #define PG8_LDB(dst, b, h) do { _Pragma("unroll") for (int n = 0; n < 2; ++n) _Pragma("unroll") for (int k = 0; k < 2; ++k) dst[n][k] = *(const LAS bf16x8*)(lds + PG8_SB(b, h) + boff + n * 2048 + k * 1024); } while (0)
; #define PG8_MMA(ai, bj, At, Bt) do { __builtin_amdgcn_s_setprio(1); _Pragma("unroll") for (int m = 0; m < 4; ++m) _Pragma("unroll") for (int n = 0; n < 2; ++n) _Pragma("unroll") for (int k = 0; k < 2; ++k) \
;         acc[ai][bj][m][n] = __builtin_amdgcn_mfma_f32_16x16x32_bf16(Bt[n][k], At[m][k], acc[ai][bj][m][n], 0, 0, 0); __builtin_amdgcn_s_setprio(0); } while (0)
; #define PG8_WAIT_V(n) asm volatile("s_waitcnt vmcnt(" #n ")" ::: "memory")
; #define PG8_BAR __builtin_amdgcn_s_barrier()
; DI void gemm_phase(LAS unsigned char* lds, int ph, unsigned char* ws, unsigned char* wg, int l, const float* pscale, int G, int cidx, int nx) {
;     ...
;         for (int t = 0; t < nt; t += 2) {
;             const bool last = (t == nt - 2);
;             const char* a1 = PG8_KA(t + 1);
;             const char* a2 = last ? nA : PG8_KA(t + 2); const char* b2 = last ? nB : PG8_KB(t + 2);
;             const char* a3 = a2 + kstep; const char* b3 = b2 + kstep;
;             if (zAb != 0 && t != 0 && (t & ntzm) == 0) { unsigned char* wsx = ws; asm volatile("" : "+s"(wsx)); int frx = fr; asm volatile("" : "+v"(frx)); merge_carry(acc, wsx, cur, (t >> lz) - 1, wr, wc, frx, fq); }
;             PG8_LDB(B0, 0, 0); PG8_LDB(B1, 0, 1); PG8_SCHED; PG8_LDA(At, 0, 0); PG8_STAGE(PG8_SA(1, 1), a1 + hstepA, voffA);
;             PG8_WAIT_V(8); PG8_WAIT_L(0); PG8_BAR; PG8_MMA(0, 0, At, B0); PG8_MMA(0, 1, At, B1); PG8_BAR; PG8_SCHED;
;             PG8_LDA(At, 0, 1); PG8_STAGE(PG8_SB(0, 0), b2, voffB); PG8_STAGE(PG8_SB(0, 1), b2 + hstepB, voffB); PG8_STAGE(PG8_SA(0, 0), a2, voffA);
;             PG8_WAIT_V(8); PG8_WAIT_L(0); PG8_BAR; PG8_MMA(1, 0, At, B0); PG8_MMA(1, 1, At, B1); PG8_BAR; PG8_SCHED;
.Lpeel_501:
.Lpeel_500:
	v_add_u32_e32 v80, s91, v173
	s_add_i32 s20, 0, 0x14000
	ds_read_b128 v[132:135], v80
	ds_read_b128 v[136:139], v80 offset:1024
	ds_read_b128 v[142:145], v80 offset:2048
	ds_read_b128 v[158:161], v80 offset:3072
	v_add_u32_e32 v80, s20, v173
	ds_read_b128 v[176:179], v80
	ds_read_b128 v[180:183], v80 offset:1024
	ds_read_b128 v[184:187], v80 offset:2048
	ds_read_b128 v[188:191], v80 offset:3072
	ds_read_b128 v[192:195], v174
	ds_read_b128 v[196:199], v174 offset:1024
	ds_read_b128 v[200:203], v174 offset:2048
	ds_read_b128 v[204:207], v174 offset:3072
	ds_read_b128 v[208:211], v174 offset:4096
	ds_read_b128 v[212:215], v174 offset:5120
	ds_read_b128 v[216:219], v174 offset:6144
	ds_read_b128 v[220:223], v174 offset:7168
	s_add_i32 m0, s79, 0xc000
	s_add_i32 s12, s38, 1
	s_lshr_b32 s18, s12, s76
	s_mul_i32 s19, s53, s18
	s_mul_hi_u32 s21, s52, s18
	s_add_i32 s21, s21, s19
	s_mul_i32 s18, s52, s18
	s_add_u32 s18, s42, s18
	s_addc_u32 s19, s43, s21
	s_and_b32 s12, s12, s83
	s_lshl_b32 s12, s12, 7
	s_add_u32 s12, s18, s12
	s_addc_u32 s19, s19, 0
	s_add_u32 s18, s12, s7
	s_addc_u32 s19, s19, 0
	global_load_lds_dwordx4 v150, s[18:19]
	s_add_i32 m0, s79, 0xe000
	s_nop 0
	global_load_lds_dwordx4 v154, s[18:19]
	s_waitcnt vmcnt(8)
	s_waitcnt lgkmcnt(0)
	s_barrier
	s_setprio 1
	s_waitcnt lgkmcnt(0)
	v_mfma_f32_16x16x32_bf16 v[128:131], v[132:135], v[192:195], 0
	s_add_i32 s0, s38, 2
	v_mfma_f32_16x16x32_bf16 v[124:127], v[142:145], v[192:195], 0
	s_lshr_b32 s1, s0, s76
	v_mfma_f32_16x16x32_bf16 v[112:115], v[132:135], v[200:203], 0
	s_mul_i32 s12, s53, s1
	v_mfma_f32_16x16x32_bf16 v[108:111], v[142:145], v[200:203], 0
	s_mul_hi_u32 s18, s52, s1
	v_mfma_f32_16x16x32_bf16 v[96:99], v[132:135], v[208:211], 0
	s_add_i32 s18, s18, s12
	v_mfma_f32_16x16x32_bf16 v[92:95], v[142:145], v[208:211], 0
	s_mul_i32 s12, s52, s1
	v_mfma_f32_16x16x32_bf16 v[76:79], v[132:135], v[216:219], 0
	s_and_b32 s0, s0, s83
	v_mfma_f32_16x16x32_bf16 v[72:75], v[142:145], v[216:219], 0
	s_lshl_b32 s0, s0, 7
	v_mfma_f32_16x16x32_bf16 v[128:131], v[136:139], v[196:199], v[128:131]
	s_mul_i32 s19, s49, s1
	v_mfma_f32_16x16x32_bf16 v[124:127], v[158:161], v[196:199], v[124:127]
	s_mul_hi_u32 s21, s48, s1
	v_mfma_f32_16x16x32_bf16 v[112:115], v[136:139], v[204:207], v[112:115]
	s_add_i32 s21, s21, s19
	v_mfma_f32_16x16x32_bf16 v[108:111], v[158:161], v[204:207], v[108:111]
	s_mul_i32 s19, s48, s1
	v_mfma_f32_16x16x32_bf16 v[96:99], v[136:139], v[212:215], v[96:99]
	s_add_u32 s12, s42, s12
	v_mfma_f32_16x16x32_bf16 v[92:95], v[158:161], v[212:215], v[92:95]
	s_addc_u32 s18, s43, s18
	v_mfma_f32_16x16x32_bf16 v[76:79], v[136:139], v[220:223], v[76:79]
	s_add_u32 s12, s12, s0
	v_mfma_f32_16x16x32_bf16 v[72:75], v[158:161], v[220:223], v[72:75]
	s_addc_u32 s18, s18, 0
	v_mfma_f32_16x16x32_bf16 v[120:123], v[176:179], v[192:195], 0
	s_add_u32 s19, s40, s19
	v_mfma_f32_16x16x32_bf16 v[116:119], v[184:187], v[192:195], 0
	s_addc_u32 s21, s41, s21
	v_mfma_f32_16x16x32_bf16 v[104:107], v[176:179], v[200:203], 0
	s_add_u32 s19, s19, s0
	v_mfma_f32_16x16x32_bf16 v[100:103], v[184:187], v[200:203], 0
	s_addc_u32 s21, s21, 0
	v_mfma_f32_16x16x32_bf16 v[88:91], v[176:179], v[208:211], 0
	s_cmp_eq_u32 s96, s38
	v_mfma_f32_16x16x32_bf16 v[82:85], v[184:187], v[208:211], 0
	s_cselect_b32 s0, s60, s12
	v_mfma_f32_16x16x32_bf16 v[68:71], v[176:179], v[216:219], 0
	s_cselect_b32 s1, s61, s18
	v_mfma_f32_16x16x32_bf16 v[64:67], v[184:187], v[216:219], 0
	s_cselect_b32 s64, s62, s19
	v_mfma_f32_16x16x32_bf16 v[120:123], v[180:183], v[196:199], v[120:123]
	s_cselect_b32 s65, s63, s21
	v_mfma_f32_16x16x32_bf16 v[116:119], v[188:191], v[196:199], v[116:119]
	v_mfma_f32_16x16x32_bf16 v[104:107], v[180:183], v[204:207], v[104:107]
	v_mfma_f32_16x16x32_bf16 v[100:103], v[188:191], v[204:207], v[100:103]
	v_mfma_f32_16x16x32_bf16 v[88:91], v[180:183], v[212:215], v[88:91]
	v_mfma_f32_16x16x32_bf16 v[82:85], v[188:191], v[212:215], v[82:85]
	v_mfma_f32_16x16x32_bf16 v[68:71], v[180:183], v[220:223], v[68:71]
	v_mfma_f32_16x16x32_bf16 v[64:67], v[188:191], v[220:223], v[64:67]
	s_setprio 0
	s_barrier
	s_add_i32 s12, s91, s78
	s_mov_b32 m0, s12
	ds_read_b128 v[192:195], v174 offset:16384
	ds_read_b128 v[196:199], v174 offset:17408
	ds_read_b128 v[200:203], v174 offset:18432
	ds_read_b128 v[204:207], v174 offset:19456
	ds_read_b128 v[208:211], v174 offset:20480
	ds_read_b128 v[212:215], v174 offset:21504
	ds_read_b128 v[216:219], v174 offset:22528
	ds_read_b128 v[220:223], v174 offset:23552
	global_load_lds_dwordx4 v152, s[64:65]
	s_add_i32 m0, s12, 0x2000
	s_add_u32 s18, s64, s77
	s_addc_u32 s19, s65, 0
	s_add_i32 s12, s20, s78
	global_load_lds_dwordx4 v156, s[64:65]
	s_mov_b32 m0, s12
	s_nop 0
	global_load_lds_dwordx4 v152, s[18:19]
	s_add_i32 m0, s12, 0x2000
	s_nop 0
	global_load_lds_dwordx4 v156, s[18:19]
	s_mov_b32 m0, s79
	s_nop 0
	global_load_lds_dwordx4 v150, s[0:1]
	s_mov_b32 m0, s80
	s_nop 0
	global_load_lds_dwordx4 v154, s[0:1]
	s_waitcnt vmcnt(8)
	s_waitcnt lgkmcnt(0)
	s_barrier
; #define PG8_STAGE(bufoff, gbase, voff) do { _Pragma("unroll") for (int _i = 0; _i < 2; ++_i) \
;         __builtin_amdgcn_global_load_lds((const unsigned*)((const char*)(gbase) + (voff)[_i]), (LAS unsigned*)(lds + (bufoff) + ldsw + _i * 8192), 16, 0, 0); } while (0)
; #define PG8_LDA(dst, b, h) do { _Pragma("unroll") for (int m = 0; m < 4; ++m) _Pragma("unroll") for (int k = 0; k < 2; ++k) dst[m][k] = *(const LAS bf16x8*)(lds + PG8_SA(b, h) + aoff + m * 2048 + k * 1024); } while (0)
; #define PG8_LDB(dst, b, h) do { _Pragma("unroll") for (int n = 0; n < 2; ++n) _Pragma("unroll") for (int k = 0; k < 2; ++k) dst[n][k] = *(const LAS bf16x8*)(lds + PG8_SB(b, h) + boff + n * 2048 + k * 1024); } while (0)
; #define PG8_MMA(ai, bj, At, Bt) do { __builtin_amdgcn_s_setprio(1); _Pragma("unroll") for (int m = 0; m < 4; ++m) _Pragma("unroll") for (int n = 0; n < 2; ++n) _Pragma("unroll") for (int k = 0; k < 2; ++k) \
;         acc[ai][bj][m][n] = __builtin_amdgcn_mfma_f32_16x16x32_bf16(Bt[n][k], At[m][k], acc[ai][bj][m][n], 0, 0, 0); __builtin_amdgcn_s_setprio(0); } while (0)
; #define PG8_WAIT_V(n) asm volatile("s_waitcnt vmcnt(" #n ")" ::: "memory")
; #define PG8_WAIT_L(n) asm volatile("s_waitcnt lgkmcnt(" #n ")" ::: "memory")
; #define PG8_BAR __builtin_amdgcn_s_barrier()
; #define PG8_SCHED __builtin_amdgcn_sched_barrier(0)
; DI void gemm_phase(LAS unsigned char* lds, int ph, unsigned char* ws, unsigned char* wg, int l, const float* pscale, int G, int cidx, int nx) {
;     ...
;             PG8_WAIT_V(8); PG8_WAIT_L(0); PG8_BAR; PG8_MMA(1, 0, At, B0); PG8_MMA(1, 1, At, B1); PG8_BAR; PG8_SCHED;
;             PG8_LDB(B0, 1, 0); PG8_LDB(B1, 1, 1); PG8_SCHED; PG8_LDA(At, 1, 0); PG8_STAGE(PG8_SA(0, 1), a2 + hstepA, voffA);
;             PG8_WAIT_V(8); PG8_WAIT_L(0); PG8_BAR; PG8_MMA(0, 0, At, B0); PG8_MMA(0, 1, At, B1); PG8_BAR; PG8_SCHED;
	s_setprio 1
	s_waitcnt lgkmcnt(0)
	v_mfma_f32_16x16x32_bf16 v[60:63], v[132:135], v[192:195], 0
	v_mfma_f32_16x16x32_bf16 v[56:59], v[142:145], v[192:195], 0
	v_mfma_f32_16x16x32_bf16 v[44:47], v[132:135], v[200:203], 0
	v_mfma_f32_16x16x32_bf16 v[40:43], v[142:145], v[200:203], 0
	v_mfma_f32_16x16x32_bf16 v[28:31], v[132:135], v[208:211], 0
	v_mfma_f32_16x16x32_bf16 v[24:27], v[142:145], v[208:211], 0
	v_mfma_f32_16x16x32_bf16 v[12:15], v[132:135], v[216:219], 0
	v_mfma_f32_16x16x32_bf16 v[8:11], v[142:145], v[216:219], 0
	v_mfma_f32_16x16x32_bf16 v[60:63], v[136:139], v[196:199], v[60:63]
	v_mfma_f32_16x16x32_bf16 v[56:59], v[158:161], v[196:199], v[56:59]
	v_mfma_f32_16x16x32_bf16 v[44:47], v[136:139], v[204:207], v[44:47]
	v_mfma_f32_16x16x32_bf16 v[40:43], v[158:161], v[204:207], v[40:43]
	v_mfma_f32_16x16x32_bf16 v[28:31], v[136:139], v[212:215], v[28:31]
	v_mfma_f32_16x16x32_bf16 v[24:27], v[158:161], v[212:215], v[24:27]
	v_mfma_f32_16x16x32_bf16 v[12:15], v[136:139], v[220:223], v[12:15]
	v_mfma_f32_16x16x32_bf16 v[8:11], v[158:161], v[220:223], v[8:11]
	v_mfma_f32_16x16x32_bf16 v[52:55], v[176:179], v[192:195], 0
	v_mfma_f32_16x16x32_bf16 v[48:51], v[184:187], v[192:195], 0
	v_mfma_f32_16x16x32_bf16 v[36:39], v[176:179], v[200:203], 0
	v_mfma_f32_16x16x32_bf16 v[32:35], v[184:187], v[200:203], 0
	v_mfma_f32_16x16x32_bf16 v[20:23], v[176:179], v[208:211], 0
	v_mfma_f32_16x16x32_bf16 v[16:19], v[184:187], v[208:211], 0
	v_mfma_f32_16x16x32_bf16 v[4:7], v[176:179], v[216:219], 0
	v_mfma_f32_16x16x32_bf16 v[0:3], v[184:187], v[216:219], 0
	v_mfma_f32_16x16x32_bf16 v[52:55], v[180:183], v[196:199], v[52:55]
	v_mfma_f32_16x16x32_bf16 v[48:51], v[188:191], v[196:199], v[48:51]
	v_mfma_f32_16x16x32_bf16 v[36:39], v[180:183], v[204:207], v[36:39]
	v_mfma_f32_16x16x32_bf16 v[32:35], v[188:191], v[204:207], v[32:35]
	v_mfma_f32_16x16x32_bf16 v[20:23], v[180:183], v[212:215], v[20:23]
	v_mfma_f32_16x16x32_bf16 v[16:19], v[188:191], v[212:215], v[16:19]
	v_mfma_f32_16x16x32_bf16 v[4:7], v[180:183], v[220:223], v[4:7]
	v_mfma_f32_16x16x32_bf16 v[0:3], v[188:191], v[220:223], v[0:3]
	s_setprio 0
	s_barrier
	s_add_i32 s12, 0, 0x18000
	v_add_u32_e32 v80, s12, v173
	s_add_i32 s18, 0, 0x1c000
	ds_read_b128 v[132:135], v80
	ds_read_b128 v[136:139], v80 offset:1024
	ds_read_b128 v[142:145], v80 offset:2048
	ds_read_b128 v[158:161], v80 offset:3072
	v_add_u32_e32 v80, s18, v173
	ds_read_b128 v[176:179], v80
	ds_read_b128 v[180:183], v80 offset:1024
	ds_read_b128 v[184:187], v80 offset:2048
	ds_read_b128 v[188:191], v80 offset:3072
	s_add_u32 s0, s0, s7
	s_addc_u32 s1, s1, 0
	s_mov_b32 m0, s81
	ds_read_b128 v[192:195], v174 offset:32768
	ds_read_b128 v[196:199], v174 offset:33792
	ds_read_b128 v[200:203], v174 offset:34816
	ds_read_b128 v[204:207], v174 offset:35840
	ds_read_b128 v[208:211], v174 offset:36864
	ds_read_b128 v[212:215], v174 offset:37888
	ds_read_b128 v[216:219], v174 offset:38912
	ds_read_b128 v[220:223], v174 offset:39936
	global_load_lds_dwordx4 v150, s[0:1]
	s_mov_b32 m0, s82
	s_nop 0
	global_load_lds_dwordx4 v154, s[0:1]
	s_waitcnt vmcnt(8)
	s_waitcnt lgkmcnt(0)
	s_barrier
	s_setprio 1
	s_waitcnt lgkmcnt(0)
	v_mfma_f32_16x16x32_bf16 v[128:131], v[132:135], v[192:195], v[128:131]
	s_sub_u32 s20, s0, s7
	v_mfma_f32_16x16x32_bf16 v[124:127], v[142:145], v[192:195], v[124:127]
	s_subb_u32 s21, s1, 0
	v_mfma_f32_16x16x32_bf16 v[112:115], v[132:135], v[200:203], v[112:115]
	s_add_u32 s20, s20, s4
	v_mfma_f32_16x16x32_bf16 v[108:111], v[142:145], v[200:203], v[108:111]
	s_addc_u32 s21, s21, s5
	v_mfma_f32_16x16x32_bf16 v[96:99], v[132:135], v[208:211], v[96:99]
	s_add_u32 s0, s64, s4
	v_mfma_f32_16x16x32_bf16 v[92:95], v[142:145], v[208:211], v[92:95]
	s_addc_u32 s1, s65, s5
	v_mfma_f32_16x16x32_bf16 v[76:79], v[132:135], v[216:219], v[76:79]
	v_mfma_f32_16x16x32_bf16 v[72:75], v[142:145], v[216:219], v[72:75]
	v_mfma_f32_16x16x32_bf16 v[128:131], v[136:139], v[196:199], v[128:131]
	v_mfma_f32_16x16x32_bf16 v[124:127], v[158:161], v[196:199], v[124:127]
	v_mfma_f32_16x16x32_bf16 v[112:115], v[136:139], v[204:207], v[112:115]
	v_mfma_f32_16x16x32_bf16 v[108:111], v[158:161], v[204:207], v[108:111]
	v_mfma_f32_16x16x32_bf16 v[96:99], v[136:139], v[212:215], v[96:99]
	v_mfma_f32_16x16x32_bf16 v[92:95], v[158:161], v[212:215], v[92:95]
	v_mfma_f32_16x16x32_bf16 v[76:79], v[136:139], v[220:223], v[76:79]
	v_mfma_f32_16x16x32_bf16 v[72:75], v[158:161], v[220:223], v[72:75]
	v_mfma_f32_16x16x32_bf16 v[120:123], v[176:179], v[192:195], v[120:123]
	v_mfma_f32_16x16x32_bf16 v[116:119], v[184:187], v[192:195], v[116:119]
	v_mfma_f32_16x16x32_bf16 v[104:107], v[176:179], v[200:203], v[104:107]
	v_mfma_f32_16x16x32_bf16 v[100:103], v[184:187], v[200:203], v[100:103]
	v_mfma_f32_16x16x32_bf16 v[86:89], v[176:179], v[208:211], v[88:91]
	v_mfma_f32_16x16x32_bf16 v[82:85], v[184:187], v[208:211], v[82:85]
	v_mfma_f32_16x16x32_bf16 v[68:71], v[176:179], v[216:219], v[68:71]
	v_mfma_f32_16x16x32_bf16 v[64:67], v[184:187], v[216:219], v[64:67]
	v_mfma_f32_16x16x32_bf16 v[120:123], v[180:183], v[196:199], v[120:123]
	v_mfma_f32_16x16x32_bf16 v[116:119], v[188:191], v[196:199], v[116:119]
	v_mfma_f32_16x16x32_bf16 v[104:107], v[180:183], v[204:207], v[104:107]
	v_mfma_f32_16x16x32_bf16 v[100:103], v[188:191], v[204:207], v[100:103]
	v_mfma_f32_16x16x32_bf16 v[88:91], v[180:183], v[212:215], v[86:89]
	v_mfma_f32_16x16x32_bf16 v[84:87], v[188:191], v[212:215], v[82:85]
	v_mfma_f32_16x16x32_bf16 v[68:71], v[180:183], v[220:223], v[68:71]
	v_mfma_f32_16x16x32_bf16 v[64:67], v[188:191], v[220:223], v[64:67]
	s_setprio 0
	s_barrier
; #define PG8_STAGE(bufoff, gbase, voff) do { _Pragma("unroll") for (int _i = 0; _i < 2; ++_i) \
;         __builtin_amdgcn_global_load_lds((const unsigned*)((const char*)(gbase) + (voff)[_i]), (LAS unsigned*)(lds + (bufoff) + ldsw + _i * 8192), 16, 0, 0); } while (0)
; #define PG8_LDA(dst, b, h) do { _Pragma("unroll") for (int m = 0; m < 4; ++m) _Pragma("unroll") for (int k = 0; k < 2; ++k) dst[m][k] = *(const LAS bf16x8*)(lds + PG8_SA(b, h) + aoff + m * 2048 + k * 1024); } while (0)
; #define PG8_LDB(dst, b, h) do { _Pragma("unroll") for (int n = 0; n < 2; ++n) _Pragma("unroll") for (int k = 0; k < 2; ++k) dst[n][k] = *(const LAS bf16x8*)(lds + PG8_SB(b, h) + boff + n * 2048 + k * 1024); } while (0)
; #define PG8_MMA(ai, bj, At, Bt) do { __builtin_amdgcn_s_setprio(1); _Pragma("unroll") for (int m = 0; m < 4; ++m) _Pragma("unroll") for (int n = 0; n < 2; ++n) _Pragma("unroll") for (int k = 0; k < 2; ++k) \
;         acc[ai][bj][m][n] = __builtin_amdgcn_mfma_f32_16x16x32_bf16(Bt[n][k], At[m][k], acc[ai][bj][m][n], 0, 0, 0); __builtin_amdgcn_s_setprio(0); } while (0)
; #define PG8_WAIT_V(n) asm volatile("s_waitcnt vmcnt(" #n ")" ::: "memory")
; #define PG8_BAR __builtin_amdgcn_s_barrier()
; DI void gemm_phase(LAS unsigned char* lds, int ph, unsigned char* ws, unsigned char* wg, int l, const float* pscale, int G, int cidx, int nx) {
;     ...
;         for (int t = 0; t < nt; t += 2) {
;             const bool last = (t == nt - 2);
;             const char* a1 = PG8_KA(t + 1);
;             const char* a2 = last ? nA : PG8_KA(t + 2); const char* b2 = last ? nB : PG8_KB(t + 2);
;             const char* a3 = a2 + kstep; const char* b3 = b2 + kstep;
;             if (zAb != 0 && t != 0 && (t & ntzm) == 0) { unsigned char* wsx = ws; asm volatile("" : "+s"(wsx)); int frx = fr; asm volatile("" : "+v"(frx)); merge_carry(acc, wsx, cur, (t >> lz) - 1, wr, wc, frx, fq); }
;             PG8_LDB(B0, 0, 0); PG8_LDB(B1, 0, 1); PG8_SCHED; PG8_LDA(At, 0, 0); PG8_STAGE(PG8_SA(1, 1), a1 + hstepA, voffA);
;             PG8_WAIT_V(8); PG8_WAIT_L(0); PG8_BAR; PG8_MMA(0, 0, At, B0); PG8_MMA(0, 1, At, B1); PG8_BAR; PG8_SCHED;
;     ...
;             PG8_LDA(At, 1, 1); PG8_STAGE(PG8_SB(1, 0), b3, voffB); PG8_STAGE(PG8_SB(1, 1), b3 + hstepB, voffB); PG8_STAGE(PG8_SA(1, 0), a3, voffA);
;             PG8_WAIT_V(8); PG8_WAIT_L(0); PG8_BAR; PG8_MMA(1, 0, At, B0); PG8_MMA(1, 1, At, B1); PG8_BAR; PG8_SCHED;
	s_add_i32 s19, s12, s78
	s_mov_b32 m0, s19
	ds_read_b128 v[192:195], v174 offset:49152
	ds_read_b128 v[196:199], v174 offset:50176
	ds_read_b128 v[200:203], v174 offset:51200
	ds_read_b128 v[204:207], v174 offset:52224
	ds_read_b128 v[208:211], v174 offset:53248
	ds_read_b128 v[212:215], v174 offset:54272
	ds_read_b128 v[216:219], v174 offset:55296
	ds_read_b128 v[220:223], v174 offset:56320
	global_load_lds_dwordx4 v152, s[0:1]
	s_add_i32 m0, s19, 0x2000
	s_add_i32 s19, s18, s78
	global_load_lds_dwordx4 v156, s[0:1]
	s_add_u32 s0, s0, s77
	s_addc_u32 s1, s1, 0
	s_mov_b32 m0, s19
	s_nop 0
	global_load_lds_dwordx4 v152, s[0:1]
	s_add_i32 m0, s19, 0x2000
	s_nop 0
	global_load_lds_dwordx4 v156, s[0:1]
	s_mov_b32 m0, s93
	s_nop 0
	global_load_lds_dwordx4 v150, s[20:21]
	s_mov_b32 m0, s94
	s_nop 0
	global_load_lds_dwordx4 v154, s[20:21]
	s_waitcnt vmcnt(8)
	s_waitcnt lgkmcnt(0)
	s_barrier
	s_setprio 1
	s_waitcnt lgkmcnt(0)
	v_mfma_f32_16x16x32_bf16 v[60:63], v[132:135], v[192:195], v[60:63]
	s_add_i32 s38, s38, 2
	v_mfma_f32_16x16x32_bf16 v[56:59], v[142:145], v[192:195], v[56:59]
	s_cmp_ge_u32 s38, s75
	v_mfma_f32_16x16x32_bf16 v[44:47], v[132:135], v[200:203], v[44:47]
	v_mfma_f32_16x16x32_bf16 v[40:43], v[142:145], v[200:203], v[40:43]
	v_mfma_f32_16x16x32_bf16 v[28:31], v[132:135], v[208:211], v[28:31]
	v_mfma_f32_16x16x32_bf16 v[24:27], v[142:145], v[208:211], v[24:27]
	v_mfma_f32_16x16x32_bf16 v[12:15], v[132:135], v[216:219], v[12:15]
	v_mfma_f32_16x16x32_bf16 v[8:11], v[142:145], v[216:219], v[8:11]
	v_mfma_f32_16x16x32_bf16 v[60:63], v[136:139], v[196:199], v[60:63]
	v_mfma_f32_16x16x32_bf16 v[56:59], v[158:161], v[196:199], v[56:59]
	v_mfma_f32_16x16x32_bf16 v[44:47], v[136:139], v[204:207], v[44:47]
	v_mfma_f32_16x16x32_bf16 v[40:43], v[158:161], v[204:207], v[40:43]
	v_mfma_f32_16x16x32_bf16 v[28:31], v[136:139], v[212:215], v[28:31]
	v_mfma_f32_16x16x32_bf16 v[24:27], v[158:161], v[212:215], v[24:27]
	v_mfma_f32_16x16x32_bf16 v[12:15], v[136:139], v[220:223], v[12:15]
	v_mfma_f32_16x16x32_bf16 v[8:11], v[158:161], v[220:223], v[8:11]
	v_mfma_f32_16x16x32_bf16 v[52:55], v[176:179], v[192:195], v[52:55]
	v_mfma_f32_16x16x32_bf16 v[48:51], v[184:187], v[192:195], v[48:51]
	v_mfma_f32_16x16x32_bf16 v[36:39], v[176:179], v[200:203], v[36:39]
	v_mfma_f32_16x16x32_bf16 v[32:35], v[184:187], v[200:203], v[32:35]
	v_mfma_f32_16x16x32_bf16 v[20:23], v[176:179], v[208:211], v[20:23]
	v_mfma_f32_16x16x32_bf16 v[16:19], v[184:187], v[208:211], v[16:19]
	v_mfma_f32_16x16x32_bf16 v[4:7], v[176:179], v[216:219], v[4:7]
	v_mfma_f32_16x16x32_bf16 v[0:3], v[184:187], v[216:219], v[0:3]
	v_mfma_f32_16x16x32_bf16 v[52:55], v[180:183], v[196:199], v[52:55]
	v_mfma_f32_16x16x32_bf16 v[48:51], v[188:191], v[196:199], v[48:51]
	v_mfma_f32_16x16x32_bf16 v[36:39], v[180:183], v[204:207], v[36:39]
	v_mfma_f32_16x16x32_bf16 v[32:35], v[188:191], v[204:207], v[32:35]
	v_mfma_f32_16x16x32_bf16 v[20:23], v[180:183], v[212:215], v[20:23]
	v_mfma_f32_16x16x32_bf16 v[16:19], v[188:191], v[212:215], v[16:19]
	v_mfma_f32_16x16x32_bf16 v[4:7], v[180:183], v[220:223], v[4:7]
	v_mfma_f32_16x16x32_bf16 v[0:3], v[188:191], v[220:223], v[0:3]
	s_setprio 0
	s_barrier
	s_cbranch_scc1 .LBB0_507
	s_branch .LBB0_501
.LBB0_500:
	v_add_u32_e32 v80, s91, v173
	s_add_i32 s20, 0, 0x14000
	ds_read_b128 v[132:135], v80
	ds_read_b128 v[136:139], v80 offset:1024
	ds_read_b128 v[142:145], v80 offset:2048
	ds_read_b128 v[158:161], v80 offset:3072
	v_add_u32_e32 v80, s20, v173
	ds_read_b128 v[176:179], v80
	ds_read_b128 v[180:183], v80 offset:1024
	ds_read_b128 v[184:187], v80 offset:2048
	ds_read_b128 v[188:191], v80 offset:3072
	ds_read_b128 v[192:195], v174
	ds_read_b128 v[196:199], v174 offset:1024
	ds_read_b128 v[200:203], v174 offset:2048
	ds_read_b128 v[204:207], v174 offset:3072
	ds_read_b128 v[208:211], v174 offset:4096
	ds_read_b128 v[212:215], v174 offset:5120
	ds_read_b128 v[216:219], v174 offset:6144
	ds_read_b128 v[220:223], v174 offset:7168
	s_add_i32 m0, s79, 0xc000
	s_add_i32 s12, s38, 1
	s_lshr_b32 s18, s12, s76
	s_mul_i32 s19, s53, s18
	s_mul_hi_u32 s21, s52, s18
	s_add_i32 s21, s21, s19
	s_mul_i32 s18, s52, s18
	s_add_u32 s18, s42, s18
	s_addc_u32 s19, s43, s21
	s_and_b32 s12, s12, s83
	s_lshl_b32 s12, s12, 7
	s_add_u32 s12, s18, s12
	s_addc_u32 s19, s19, 0
	s_add_u32 s18, s12, s7
	s_addc_u32 s19, s19, 0
	global_load_lds_dwordx4 v150, s[18:19]
	s_add_i32 m0, s79, 0xe000
	s_nop 0
	global_load_lds_dwordx4 v154, s[18:19]
	s_waitcnt vmcnt(8)
	s_waitcnt lgkmcnt(0)
	s_barrier
; #define PG8_STAGE(bufoff, gbase, voff) do { _Pragma("unroll") for (int _i = 0; _i < 2; ++_i) \
;         __builtin_amdgcn_global_load_lds((const unsigned*)((const char*)(gbase) + (voff)[_i]), (LAS unsigned*)(lds + (bufoff) + ldsw + _i * 8192), 16, 0, 0); } while (0)
; #define PG8_LDA(dst, b, h) do { _Pragma("unroll") for (int m = 0; m < 4; ++m) _Pragma("unroll") for (int k = 0; k < 2; ++k) dst[m][k] = *(const LAS bf16x8*)(lds + PG8_SA(b, h) + aoff + m * 2048 + k * 1024); } while (0)
; #define PG8_MMA(ai, bj, At, Bt) do { __builtin_amdgcn_s_setprio(1); _Pragma("unroll") for (int m = 0; m < 4; ++m) _Pragma("unroll") for (int n = 0; n < 2; ++n) _Pragma("unroll") for (int k = 0; k < 2; ++k) \
;         acc[ai][bj][m][n] = __builtin_amdgcn_mfma_f32_16x16x32_bf16(Bt[n][k], At[m][k], acc[ai][bj][m][n], 0, 0, 0); __builtin_amdgcn_s_setprio(0); } while (0)
; #define PG8_WAIT_V(n) asm volatile("s_waitcnt vmcnt(" #n ")" ::: "memory")
; #define PG8_WAIT_L(n) asm volatile("s_waitcnt lgkmcnt(" #n ")" ::: "memory")
; #define PG8_BAR __builtin_amdgcn_s_barrier()
; #define PG8_SCHED __builtin_amdgcn_sched_barrier(0)
; DI void gemm_phase(LAS unsigned char* lds, int ph, unsigned char* ws, unsigned char* wg, int l, const float* pscale, int G, int cidx, int nx) {
;     ...
;             PG8_WAIT_V(8); PG8_WAIT_L(0); PG8_BAR; PG8_MMA(0, 0, At, B0); PG8_MMA(0, 1, At, B1); PG8_BAR; PG8_SCHED;
;             PG8_LDA(At, 0, 1); PG8_STAGE(PG8_SB(0, 0), b2, voffB); PG8_STAGE(PG8_SB(0, 1), b2 + hstepB, voffB); PG8_STAGE(PG8_SA(0, 0), a2, voffA);
;             PG8_WAIT_V(8); PG8_WAIT_L(0); PG8_BAR; PG8_MMA(1, 0, At, B0); PG8_MMA(1, 1, At, B1); PG8_BAR; PG8_SCHED;
	s_setprio 1
	s_waitcnt lgkmcnt(0)
	v_mfma_f32_16x16x32_bf16 v[128:131], v[132:135], v[192:195], v[128:131]
	s_add_i32 s0, s38, 2
	v_mfma_f32_16x16x32_bf16 v[124:127], v[142:145], v[192:195], v[124:127]
	s_lshr_b32 s1, s0, s76
	v_mfma_f32_16x16x32_bf16 v[112:115], v[132:135], v[200:203], v[112:115]
	s_mul_i32 s12, s53, s1
	v_mfma_f32_16x16x32_bf16 v[108:111], v[142:145], v[200:203], v[108:111]
	s_mul_hi_u32 s18, s52, s1
	v_mfma_f32_16x16x32_bf16 v[96:99], v[132:135], v[208:211], v[96:99]
	s_add_i32 s18, s18, s12
	v_mfma_f32_16x16x32_bf16 v[92:95], v[142:145], v[208:211], v[92:95]
	s_mul_i32 s12, s52, s1
	v_mfma_f32_16x16x32_bf16 v[76:79], v[132:135], v[216:219], v[76:79]
	s_and_b32 s0, s0, s83
	v_mfma_f32_16x16x32_bf16 v[72:75], v[142:145], v[216:219], v[72:75]
	s_lshl_b32 s0, s0, 7
	v_mfma_f32_16x16x32_bf16 v[128:131], v[136:139], v[196:199], v[128:131]
	s_mul_i32 s19, s49, s1
	v_mfma_f32_16x16x32_bf16 v[124:127], v[158:161], v[196:199], v[124:127]
	s_mul_hi_u32 s21, s48, s1
	v_mfma_f32_16x16x32_bf16 v[112:115], v[136:139], v[204:207], v[112:115]
	s_add_i32 s21, s21, s19
	v_mfma_f32_16x16x32_bf16 v[108:111], v[158:161], v[204:207], v[108:111]
	s_mul_i32 s19, s48, s1
	v_mfma_f32_16x16x32_bf16 v[96:99], v[136:139], v[212:215], v[96:99]
	s_add_u32 s12, s42, s12
	v_mfma_f32_16x16x32_bf16 v[92:95], v[158:161], v[212:215], v[92:95]
	s_addc_u32 s18, s43, s18
	v_mfma_f32_16x16x32_bf16 v[76:79], v[136:139], v[220:223], v[76:79]
	s_add_u32 s12, s12, s0
	v_mfma_f32_16x16x32_bf16 v[72:75], v[158:161], v[220:223], v[72:75]
	s_addc_u32 s18, s18, 0
	v_mfma_f32_16x16x32_bf16 v[120:123], v[176:179], v[192:195], v[120:123]
	s_add_u32 s19, s40, s19
	v_mfma_f32_16x16x32_bf16 v[116:119], v[184:187], v[192:195], v[116:119]
	s_addc_u32 s21, s41, s21
	v_mfma_f32_16x16x32_bf16 v[104:107], v[176:179], v[200:203], v[104:107]
	s_add_u32 s19, s19, s0
	v_mfma_f32_16x16x32_bf16 v[100:103], v[184:187], v[200:203], v[100:103]
	s_addc_u32 s21, s21, 0
	v_mfma_f32_16x16x32_bf16 v[88:91], v[176:179], v[208:211], v[88:91]
	s_cmp_eq_u32 s96, s38
	v_mfma_f32_16x16x32_bf16 v[82:85], v[184:187], v[208:211], v[84:87]
	s_cselect_b32 s0, s60, s12
	v_mfma_f32_16x16x32_bf16 v[68:71], v[176:179], v[216:219], v[68:71]
	s_cselect_b32 s1, s61, s18
	v_mfma_f32_16x16x32_bf16 v[64:67], v[184:187], v[216:219], v[64:67]
	s_cselect_b32 s64, s62, s19
	v_mfma_f32_16x16x32_bf16 v[120:123], v[180:183], v[196:199], v[120:123]
	s_cselect_b32 s65, s63, s21
	v_mfma_f32_16x16x32_bf16 v[116:119], v[188:191], v[196:199], v[116:119]
	v_mfma_f32_16x16x32_bf16 v[104:107], v[180:183], v[204:207], v[104:107]
	v_mfma_f32_16x16x32_bf16 v[100:103], v[188:191], v[204:207], v[100:103]
	v_mfma_f32_16x16x32_bf16 v[88:91], v[180:183], v[212:215], v[88:91]
	v_mfma_f32_16x16x32_bf16 v[82:85], v[188:191], v[212:215], v[82:85]
	v_mfma_f32_16x16x32_bf16 v[68:71], v[180:183], v[220:223], v[68:71]
	v_mfma_f32_16x16x32_bf16 v[64:67], v[188:191], v[220:223], v[64:67]
	s_setprio 0
	s_barrier
	s_add_i32 s12, s91, s78
	s_mov_b32 m0, s12
	ds_read_b128 v[192:195], v174 offset:16384
	ds_read_b128 v[196:199], v174 offset:17408
	ds_read_b128 v[200:203], v174 offset:18432
	ds_read_b128 v[204:207], v174 offset:19456
	ds_read_b128 v[208:211], v174 offset:20480
	ds_read_b128 v[212:215], v174 offset:21504
	ds_read_b128 v[216:219], v174 offset:22528
	ds_read_b128 v[220:223], v174 offset:23552
	global_load_lds_dwordx4 v152, s[64:65]
	s_add_i32 m0, s12, 0x2000
	s_add_u32 s18, s64, s77
	s_addc_u32 s19, s65, 0
	s_add_i32 s12, s20, s78
	global_load_lds_dwordx4 v156, s[64:65]
	s_mov_b32 m0, s12
	s_nop 0
	global_load_lds_dwordx4 v152, s[18:19]
	s_add_i32 m0, s12, 0x2000
	s_nop 0
	global_load_lds_dwordx4 v156, s[18:19]
	s_mov_b32 m0, s79
	s_nop 0
	global_load_lds_dwordx4 v150, s[0:1]
	s_mov_b32 m0, s80
	s_nop 0
	global_load_lds_dwordx4 v154, s[0:1]
	s_waitcnt vmcnt(8)
	s_waitcnt lgkmcnt(0)
	s_barrier
	s_setprio 1
	s_waitcnt lgkmcnt(0)
	v_mfma_f32_16x16x32_bf16 v[60:63], v[132:135], v[192:195], v[60:63]
	v_mfma_f32_16x16x32_bf16 v[56:59], v[142:145], v[192:195], v[56:59]
	v_mfma_f32_16x16x32_bf16 v[44:47], v[132:135], v[200:203], v[44:47]
	v_mfma_f32_16x16x32_bf16 v[40:43], v[142:145], v[200:203], v[40:43]
	v_mfma_f32_16x16x32_bf16 v[28:31], v[132:135], v[208:211], v[28:31]
	v_mfma_f32_16x16x32_bf16 v[24:27], v[142:145], v[208:211], v[24:27]
	v_mfma_f32_16x16x32_bf16 v[12:15], v[132:135], v[216:219], v[12:15]
	v_mfma_f32_16x16x32_bf16 v[8:11], v[142:145], v[216:219], v[8:11]
	v_mfma_f32_16x16x32_bf16 v[60:63], v[136:139], v[196:199], v[60:63]
	v_mfma_f32_16x16x32_bf16 v[56:59], v[158:161], v[196:199], v[56:59]
	v_mfma_f32_16x16x32_bf16 v[44:47], v[136:139], v[204:207], v[44:47]
	v_mfma_f32_16x16x32_bf16 v[40:43], v[158:161], v[204:207], v[40:43]
	v_mfma_f32_16x16x32_bf16 v[28:31], v[136:139], v[212:215], v[28:31]
	v_mfma_f32_16x16x32_bf16 v[24:27], v[158:161], v[212:215], v[24:27]
	v_mfma_f32_16x16x32_bf16 v[12:15], v[136:139], v[220:223], v[12:15]
	v_mfma_f32_16x16x32_bf16 v[8:11], v[158:161], v[220:223], v[8:11]
	v_mfma_f32_16x16x32_bf16 v[52:55], v[176:179], v[192:195], v[52:55]
	v_mfma_f32_16x16x32_bf16 v[48:51], v[184:187], v[192:195], v[48:51]
	v_mfma_f32_16x16x32_bf16 v[36:39], v[176:179], v[200:203], v[36:39]
	v_mfma_f32_16x16x32_bf16 v[32:35], v[184:187], v[200:203], v[32:35]
	v_mfma_f32_16x16x32_bf16 v[20:23], v[176:179], v[208:211], v[20:23]
	v_mfma_f32_16x16x32_bf16 v[16:19], v[184:187], v[208:211], v[16:19]
	v_mfma_f32_16x16x32_bf16 v[4:7], v[176:179], v[216:219], v[4:7]
	v_mfma_f32_16x16x32_bf16 v[0:3], v[184:187], v[216:219], v[0:3]
	v_mfma_f32_16x16x32_bf16 v[52:55], v[180:183], v[196:199], v[52:55]
	v_mfma_f32_16x16x32_bf16 v[48:51], v[188:191], v[196:199], v[48:51]
	v_mfma_f32_16x16x32_bf16 v[36:39], v[180:183], v[204:207], v[36:39]
	v_mfma_f32_16x16x32_bf16 v[32:35], v[188:191], v[204:207], v[32:35]
	v_mfma_f32_16x16x32_bf16 v[20:23], v[180:183], v[212:215], v[20:23]
	v_mfma_f32_16x16x32_bf16 v[16:19], v[188:191], v[212:215], v[16:19]
	v_mfma_f32_16x16x32_bf16 v[4:7], v[180:183], v[220:223], v[4:7]
	v_mfma_f32_16x16x32_bf16 v[0:3], v[188:191], v[220:223], v[0:3]
	s_setprio 0
	s_barrier
; #define PG8_STAGE(bufoff, gbase, voff) do { _Pragma("unroll") for (int _i = 0; _i < 2; ++_i) \
;         __builtin_amdgcn_global_load_lds((const unsigned*)((const char*)(gbase) + (voff)[_i]), (LAS unsigned*)(lds + (bufoff) + ldsw + _i * 8192), 16, 0, 0); } while (0)
; #define PG8_LDA(dst, b, h) do { _Pragma("unroll") for (int m = 0; m < 4; ++m) _Pragma("unroll") for (int k = 0; k < 2; ++k) dst[m][k] = *(const LAS bf16x8*)(lds + PG8_SA(b, h) + aoff + m * 2048 + k * 1024); } while (0)
; #define PG8_LDB(dst, b, h) do { _Pragma("unroll") for (int n = 0; n < 2; ++n) _Pragma("unroll") for (int k = 0; k < 2; ++k) dst[n][k] = *(const LAS bf16x8*)(lds + PG8_SB(b, h) + boff + n * 2048 + k * 1024); } while (0)
; #define PG8_MMA(ai, bj, At, Bt) do { __builtin_amdgcn_s_setprio(1); _Pragma("unroll") for (int m = 0; m < 4; ++m) _Pragma("unroll") for (int n = 0; n < 2; ++n) _Pragma("unroll") for (int k = 0; k < 2; ++k) \
;         acc[ai][bj][m][n] = __builtin_amdgcn_mfma_f32_16x16x32_bf16(Bt[n][k], At[m][k], acc[ai][bj][m][n], 0, 0, 0); __builtin_amdgcn_s_setprio(0); } while (0)
; #define PG8_WAIT_V(n) asm volatile("s_waitcnt vmcnt(" #n ")" ::: "memory")
; #define PG8_WAIT_L(n) asm volatile("s_waitcnt lgkmcnt(" #n ")" ::: "memory")
; #define PG8_BAR __builtin_amdgcn_s_barrier()
; #define PG8_SCHED __builtin_amdgcn_sched_barrier(0)
; DI void gemm_phase(LAS unsigned char* lds, int ph, unsigned char* ws, unsigned char* wg, int l, const float* pscale, int G, int cidx, int nx) {
;     ...
;             PG8_LDB(B0, 1, 0); PG8_LDB(B1, 1, 1); PG8_SCHED; PG8_LDA(At, 1, 0); PG8_STAGE(PG8_SA(0, 1), a2 + hstepA, voffA);
;             PG8_WAIT_V(8); PG8_WAIT_L(0); PG8_BAR; PG8_MMA(0, 0, At, B0); PG8_MMA(0, 1, At, B1); PG8_BAR; PG8_SCHED;
;             PG8_LDA(At, 1, 1); PG8_STAGE(PG8_SB(1, 0), b3, voffB); PG8_STAGE(PG8_SB(1, 1), b3 + hstepB, voffB); PG8_STAGE(PG8_SA(1, 0), a3, voffA);
;             PG8_WAIT_V(8); PG8_WAIT_L(0); PG8_BAR; PG8_MMA(1, 0, At, B0); PG8_MMA(1, 1, At, B1); PG8_BAR; PG8_SCHED;
	s_add_i32 s12, 0, 0x18000
	v_add_u32_e32 v80, s12, v173
	s_add_i32 s18, 0, 0x1c000
	ds_read_b128 v[132:135], v80
	ds_read_b128 v[136:139], v80 offset:1024
	ds_read_b128 v[142:145], v80 offset:2048
	ds_read_b128 v[158:161], v80 offset:3072
	v_add_u32_e32 v80, s18, v173
	ds_read_b128 v[176:179], v80
	ds_read_b128 v[180:183], v80 offset:1024
	ds_read_b128 v[184:187], v80 offset:2048
	ds_read_b128 v[188:191], v80 offset:3072
	s_add_u32 s0, s0, s7
	s_addc_u32 s1, s1, 0
	s_mov_b32 m0, s81
	ds_read_b128 v[192:195], v174 offset:32768
	ds_read_b128 v[196:199], v174 offset:33792
	ds_read_b128 v[200:203], v174 offset:34816
	ds_read_b128 v[204:207], v174 offset:35840
	ds_read_b128 v[208:211], v174 offset:36864
	ds_read_b128 v[212:215], v174 offset:37888
	ds_read_b128 v[216:219], v174 offset:38912
	ds_read_b128 v[220:223], v174 offset:39936
	global_load_lds_dwordx4 v150, s[0:1]
	s_mov_b32 m0, s82
	s_nop 0
	global_load_lds_dwordx4 v154, s[0:1]
	s_waitcnt vmcnt(8)
	s_waitcnt lgkmcnt(0)
	s_barrier
	s_setprio 1
	s_waitcnt lgkmcnt(0)
	v_mfma_f32_16x16x32_bf16 v[128:131], v[132:135], v[192:195], v[128:131]
	s_sub_u32 s20, s0, s7
	v_mfma_f32_16x16x32_bf16 v[124:127], v[142:145], v[192:195], v[124:127]
	s_subb_u32 s21, s1, 0
	v_mfma_f32_16x16x32_bf16 v[112:115], v[132:135], v[200:203], v[112:115]
	s_add_u32 s20, s20, s4
	v_mfma_f32_16x16x32_bf16 v[108:111], v[142:145], v[200:203], v[108:111]
	s_addc_u32 s21, s21, s5
	v_mfma_f32_16x16x32_bf16 v[96:99], v[132:135], v[208:211], v[96:99]
	s_add_u32 s0, s64, s4
	v_mfma_f32_16x16x32_bf16 v[92:95], v[142:145], v[208:211], v[92:95]
	s_addc_u32 s1, s65, s5
	v_mfma_f32_16x16x32_bf16 v[76:79], v[132:135], v[216:219], v[76:79]
	v_mfma_f32_16x16x32_bf16 v[72:75], v[142:145], v[216:219], v[72:75]
	v_mfma_f32_16x16x32_bf16 v[128:131], v[136:139], v[196:199], v[128:131]
	v_mfma_f32_16x16x32_bf16 v[124:127], v[158:161], v[196:199], v[124:127]
	v_mfma_f32_16x16x32_bf16 v[112:115], v[136:139], v[204:207], v[112:115]
	v_mfma_f32_16x16x32_bf16 v[108:111], v[158:161], v[204:207], v[108:111]
	v_mfma_f32_16x16x32_bf16 v[96:99], v[136:139], v[212:215], v[96:99]
	v_mfma_f32_16x16x32_bf16 v[92:95], v[158:161], v[212:215], v[92:95]
	v_mfma_f32_16x16x32_bf16 v[76:79], v[136:139], v[220:223], v[76:79]
	v_mfma_f32_16x16x32_bf16 v[72:75], v[158:161], v[220:223], v[72:75]
	v_mfma_f32_16x16x32_bf16 v[120:123], v[176:179], v[192:195], v[120:123]
	v_mfma_f32_16x16x32_bf16 v[116:119], v[184:187], v[192:195], v[116:119]
	v_mfma_f32_16x16x32_bf16 v[104:107], v[176:179], v[200:203], v[104:107]
	v_mfma_f32_16x16x32_bf16 v[100:103], v[184:187], v[200:203], v[100:103]
	v_mfma_f32_16x16x32_bf16 v[86:89], v[176:179], v[208:211], v[88:91]
	v_mfma_f32_16x16x32_bf16 v[82:85], v[184:187], v[208:211], v[82:85]
	v_mfma_f32_16x16x32_bf16 v[68:71], v[176:179], v[216:219], v[68:71]
	v_mfma_f32_16x16x32_bf16 v[64:67], v[184:187], v[216:219], v[64:67]
	v_mfma_f32_16x16x32_bf16 v[120:123], v[180:183], v[196:199], v[120:123]
	v_mfma_f32_16x16x32_bf16 v[116:119], v[188:191], v[196:199], v[116:119]
	v_mfma_f32_16x16x32_bf16 v[104:107], v[180:183], v[204:207], v[104:107]
	v_mfma_f32_16x16x32_bf16 v[100:103], v[188:191], v[204:207], v[100:103]
	v_mfma_f32_16x16x32_bf16 v[88:91], v[180:183], v[212:215], v[86:89]
	v_mfma_f32_16x16x32_bf16 v[84:87], v[188:191], v[212:215], v[82:85]
	v_mfma_f32_16x16x32_bf16 v[68:71], v[180:183], v[220:223], v[68:71]
	v_mfma_f32_16x16x32_bf16 v[64:67], v[188:191], v[220:223], v[64:67]
	s_setprio 0
	s_barrier
	s_add_i32 s19, s12, s78
	s_mov_b32 m0, s19
	ds_read_b128 v[192:195], v174 offset:49152
	ds_read_b128 v[196:199], v174 offset:50176
	ds_read_b128 v[200:203], v174 offset:51200
	ds_read_b128 v[204:207], v174 offset:52224
	ds_read_b128 v[208:211], v174 offset:53248
	ds_read_b128 v[212:215], v174 offset:54272
	ds_read_b128 v[216:219], v174 offset:55296
	ds_read_b128 v[220:223], v174 offset:56320
	global_load_lds_dwordx4 v152, s[0:1]
	s_add_i32 m0, s19, 0x2000
	s_add_i32 s19, s18, s78
	global_load_lds_dwordx4 v156, s[0:1]
	s_add_u32 s0, s0, s77
	s_addc_u32 s1, s1, 0
	s_mov_b32 m0, s19
	s_nop 0
	global_load_lds_dwordx4 v152, s[0:1]
	s_add_i32 m0, s19, 0x2000
	s_nop 0
	global_load_lds_dwordx4 v156, s[0:1]
	s_mov_b32 m0, s93
	s_nop 0
	global_load_lds_dwordx4 v150, s[20:21]
	s_mov_b32 m0, s94
	s_nop 0
	global_load_lds_dwordx4 v154, s[20:21]
	s_waitcnt vmcnt(8)
	s_waitcnt lgkmcnt(0)
	s_barrier
	s_setprio 1
	s_waitcnt lgkmcnt(0)
	v_mfma_f32_16x16x32_bf16 v[60:63], v[132:135], v[192:195], v[60:63]
	s_add_i32 s38, s38, 2
	v_mfma_f32_16x16x32_bf16 v[56:59], v[142:145], v[192:195], v[56:59]
	s_cmp_ge_u32 s38, s75
	v_mfma_f32_16x16x32_bf16 v[44:47], v[132:135], v[200:203], v[44:47]
	v_mfma_f32_16x16x32_bf16 v[40:43], v[142:145], v[200:203], v[40:43]
	v_mfma_f32_16x16x32_bf16 v[28:31], v[132:135], v[208:211], v[28:31]
	v_mfma_f32_16x16x32_bf16 v[24:27], v[142:145], v[208:211], v[24:27]
	v_mfma_f32_16x16x32_bf16 v[12:15], v[132:135], v[216:219], v[12:15]
	v_mfma_f32_16x16x32_bf16 v[8:11], v[142:145], v[216:219], v[8:11]
	v_mfma_f32_16x16x32_bf16 v[60:63], v[136:139], v[196:199], v[60:63]
	v_mfma_f32_16x16x32_bf16 v[56:59], v[158:161], v[196:199], v[56:59]
	v_mfma_f32_16x16x32_bf16 v[44:47], v[136:139], v[204:207], v[44:47]
	v_mfma_f32_16x16x32_bf16 v[40:43], v[158:161], v[204:207], v[40:43]
	v_mfma_f32_16x16x32_bf16 v[28:31], v[136:139], v[212:215], v[28:31]
	v_mfma_f32_16x16x32_bf16 v[24:27], v[158:161], v[212:215], v[24:27]
	v_mfma_f32_16x16x32_bf16 v[12:15], v[136:139], v[220:223], v[12:15]
	v_mfma_f32_16x16x32_bf16 v[8:11], v[158:161], v[220:223], v[8:11]
	v_mfma_f32_16x16x32_bf16 v[52:55], v[176:179], v[192:195], v[52:55]
	v_mfma_f32_16x16x32_bf16 v[48:51], v[184:187], v[192:195], v[48:51]
	v_mfma_f32_16x16x32_bf16 v[36:39], v[176:179], v[200:203], v[36:39]
	v_mfma_f32_16x16x32_bf16 v[32:35], v[184:187], v[200:203], v[32:35]
	v_mfma_f32_16x16x32_bf16 v[20:23], v[176:179], v[208:211], v[20:23]
	v_mfma_f32_16x16x32_bf16 v[16:19], v[184:187], v[208:211], v[16:19]
	v_mfma_f32_16x16x32_bf16 v[4:7], v[176:179], v[216:219], v[4:7]
	v_mfma_f32_16x16x32_bf16 v[0:3], v[184:187], v[216:219], v[0:3]
	v_mfma_f32_16x16x32_bf16 v[52:55], v[180:183], v[196:199], v[52:55]
	v_mfma_f32_16x16x32_bf16 v[48:51], v[188:191], v[196:199], v[48:51]
	v_mfma_f32_16x16x32_bf16 v[36:39], v[180:183], v[204:207], v[36:39]
	v_mfma_f32_16x16x32_bf16 v[32:35], v[188:191], v[204:207], v[32:35]
	v_mfma_f32_16x16x32_bf16 v[20:23], v[180:183], v[212:215], v[20:23]
	v_mfma_f32_16x16x32_bf16 v[16:19], v[188:191], v[212:215], v[16:19]
	v_mfma_f32_16x16x32_bf16 v[4:7], v[180:183], v[220:223], v[4:7]
	v_mfma_f32_16x16x32_bf16 v[0:3], v[188:191], v[220:223], v[0:3]
	s_setprio 0
	s_barrier
	s_cbranch_scc1 .LBB0_507
